# P3 output stores and P4 final stores use the default cache policy instead of nt
# speedup vs baseline: 1.0031x; 1.0031x over previous
.LBB0_384:
	s_waitcnt vmcnt(0)
	s_waitcnt lgkmcnt(0)
	s_barrier
	s_cmpk_eq_i32 s44, 0xf000
	s_cbranch_scc1 .LBB0_386
	s_add_u32 s2, s8, s48
	s_addc_u32 s3, s9, 0
	ds_read_b128 v[34:37], v104 offset:16384
	v_lshl_add_u64 v[38:39], s[2:3], 0, v[50:51]
	v_lshlrev_b64 v[38:39], 12, v[38:39]
	v_lshl_add_u64 v[42:43], v[52:53], 0, v[38:39]
	ds_read_b128 v[38:41], v105 offset:16384
	s_waitcnt lgkmcnt(1)
	global_store_dwordx4 v[42:43], v[34:37], off
	s_nop 1
	v_lshl_add_u64 v[34:35], s[2:3], 0, v[54:55]
	v_lshlrev_b64 v[34:35], 12, v[34:35]
	v_lshl_add_u64 v[34:35], v[52:53], 0, v[34:35]
	s_waitcnt lgkmcnt(0)
	global_store_dwordx4 v[34:35], v[38:41], off

.LBB0_450:
	v_bitop3_b32 v3, s33, v0, v123 bitop3:0x36
	v_or_b32_e32 v6, s33, v123
	v_mov_b32_e32 v11, 0
	v_lshlrev_b32_e32 v3, 4, v3
	s_or_b32 s8, s8, 0x1c0
	v_and_b32_e32 v10, 0xf0, v202
	v_lshlrev_b32_e32 v2, 8, v6
	v_and_b32_e32 v3, 0xf0, v3
	v_mov_b32_e32 v7, v11
	s_waitcnt lgkmcnt(0)
	s_barrier
	v_lshl_add_u64 v[12:13], s[12:13], 0, v[10:11]
	v_add3_u32 v2, 0, v3, v2
	v_lshl_add_u64 v[8:9], s[8:9], 0, v[6:7]
	v_or_b32_e32 v10, 4, v6
	v_bitop3_b32 v6, v6, v0, 4 bitop3:0x36
	ds_read_b128 v[2:5], v2 offset:16384
	v_lshlrev_b32_e32 v6, 4, v6
	v_lshlrev_b32_e32 v7, 8, v10
	v_and_b32_e32 v6, 0xf0, v6
	v_lshlrev_b64 v[8:9], 12, v[8:9]
	v_add3_u32 v6, 0, v6, v7
	v_lshl_add_u64 v[14:15], v[12:13], 0, v[8:9]
	ds_read_b128 v[6:9], v6 offset:16384
	s_waitcnt lgkmcnt(1)
	global_store_dwordx4 v[14:15], v[2:5], off
	s_cmpk_lt_i32 s65, 0x100
	v_readfirstlane_b32 s6, v0
	v_lshl_add_u64 v[2:3], s[8:9], 0, v[10:11]
	v_lshlrev_b64 v[2:3], 12, v[2:3]
	v_lshl_add_u64 v[2:3], v[12:13], 0, v[2:3]
	s_waitcnt lgkmcnt(0)
	global_store_dwordx4 v[2:3], v[6:9], off
	v_lshrrev_b32_e32 v2, 1, v232
	v_lshlrev_b32_e32 v3, 5, v239
	v_and_or_b32 v3, v3, 32, v2
	v_lshlrev_b32_e32 v239, 1, v3
	v_lshlrev_b32_e32 v3, 5, v242
	s_waitcnt vmcnt(0)
	v_and_or_b32 v3, v3, 32, v2
	v_lshl_or_b32 v204, v240, 12, v239
	v_lshlrev_b32_e32 v240, 1, v3
	v_lshl_or_b32 v202, v229, 12, v239
	v_lshl_or_b32 v208, v243, 12, v240
	s_cselect_b64 s[4:5], -1, 0
	s_cmpk_gt_i32 s65, 0xff
	v_lshl_or_b32 v210, v241, 12, v240
	s_barrier
	s_cbranch_scc1 .LBB0_459
	s_ashr_i32 s0, s65, 31
	s_lshr_b32 s0, s0, 29
	s_add_i32 s2, s65, s0
	s_and_b32 s0, s2, -8
	s_sub_i32 s3, s65, s0
	s_cmp_gt_i32 s3, -1
	s_cbranch_scc0 .LBB0_453
	s_lshl_b32 s8, s3, 5
	s_cbranch_execz .LBB0_454
	s_branch .LBB0_455

.LBB0_549:
	s_cmp_lg_u32 s58, 0
	s_cselect_b64 s[6:7], -1, 0
	s_and_b64 vcc, exec, s[6:7]
	s_cbranch_vccz .LBB0_557
	s_lshl_b32 s3, s42, 3
	s_lshl_b32 s2, s40, 5
	s_add_i32 s3, s3, s21
	s_add_i32 s2, s3, s2
	s_ashr_i32 s3, s2, 31
	s_lshl_b64 s[2:3], s[2:3], 13
	v_lshl_add_u64 v[134:135], v[200:201], 0, s[2:3]
	s_mov_b64 s[2:3], 0x1000
	v_lshl_add_u64 v[136:137], v[134:135], 0, s[2:3]
	global_load_dwordx2 v[150:151], v[134:135], off
	global_load_dwordx2 v[152:153], v[134:135], off offset:512
	global_load_dwordx2 v[154:155], v[134:135], off offset:1024
	global_load_dwordx2 v[156:157], v[134:135], off offset:1536
	global_load_dwordx2 v[158:159], v[134:135], off offset:2048
	global_load_dwordx2 v[160:161], v[134:135], off offset:2560
	global_load_dwordx2 v[162:163], v[134:135], off offset:3072
	global_load_dwordx2 v[164:165], v[134:135], off offset:3584
	global_load_dwordx2 v[166:167], v[136:137], off
	global_load_dwordx2 v[168:169], v[136:137], off offset:512
	global_load_dwordx2 v[170:171], v[136:137], off offset:1024
	global_load_dwordx2 v[172:173], v[136:137], off offset:1536
	global_load_dwordx2 v[174:175], v[136:137], off offset:2048
	global_load_dwordx2 v[176:177], v[136:137], off offset:2560
	global_load_dwordx2 v[178:179], v[136:137], off offset:3072
	global_load_dwordx2 v[180:181], v[136:137], off offset:3584
	v_lshl_add_u32 v138, s40, 8, v242
	v_lshl_or_b32 v148, s42, 8, v243
	v_ashrrev_i32_e32 v139, 31, v138
	v_ashrrev_i32_e32 v149, 31, v148
	v_lshlrev_b64 v[148:149], 1, v[148:149]
	v_lshlrev_b64 v[138:139], 11, v[138:139]
	v_lshl_add_u64 v[138:139], s[10:11], 0, v[138:139]
	v_lshl_add_u64 v[138:139], v[138:139], 0, v[148:149]
	s_waitcnt vmcnt(0)
	v_mov_b64_e32 v[140:141], v[138:139]
	v_cvt_f32_ubyte0_e32 v182, v150
	v_cvt_f32_ubyte1_e32 v183, v150
	v_cvt_f32_ubyte2_e32 v184, v150
	v_cvt_f32_ubyte3_e32 v185, v150
	v_cvt_f32_ubyte0_e32 v186, v151
	v_cvt_f32_ubyte1_e32 v187, v151
	v_cvt_f32_ubyte2_e32 v188, v151
	v_cvt_f32_ubyte3_e32 v189, v151
	v_pk_mul_f32 v[182:183], v[182:183], s[20:21] op_sel_hi:[1,0]
	v_pk_mul_f32 v[184:185], v[184:185], s[20:21] op_sel_hi:[1,0]
	v_pk_mul_f32 v[186:187], v[186:187], s[20:21] op_sel_hi:[1,0]
	v_pk_mul_f32 v[188:189], v[188:189], s[20:21] op_sel_hi:[1,0]
	v_pk_mul_f32 v[182:183], v[130:131], v[182:183]
	v_pk_mul_f32 v[184:185], v[132:133], v[184:185]
	v_pk_mul_f32 v[186:187], v[126:127], v[186:187]
	v_pk_mul_f32 v[188:189], v[128:129], v[188:189]
	v_cvt_pk_bf16_f32 v190, v182, v183
	v_cvt_pk_bf16_f32 v191, v184, v185
	v_cvt_pk_bf16_f32 v192, v186, v187
	v_cvt_pk_bf16_f32 v193, v188, v189
	ds_bpermute_b32 v194, v241, v190
	ds_bpermute_b32 v195, v241, v191
	ds_bpermute_b32 v196, v241, v192
	ds_bpermute_b32 v197, v241, v193
	v_cvt_f32_ubyte0_e32 v222, v152
	v_cvt_f32_ubyte1_e32 v223, v152
	v_cvt_f32_ubyte2_e32 v224, v152
	v_cvt_f32_ubyte3_e32 v225, v152
	v_cvt_f32_ubyte0_e32 v226, v153
	v_cvt_f32_ubyte1_e32 v227, v153
	v_cvt_f32_ubyte2_e32 v228, v153
	v_cvt_f32_ubyte3_e32 v229, v153
	v_pk_mul_f32 v[222:223], v[222:223], s[20:21] op_sel_hi:[1,0]
	v_pk_mul_f32 v[224:225], v[224:225], s[20:21] op_sel_hi:[1,0]
	v_pk_mul_f32 v[226:227], v[226:227], s[20:21] op_sel_hi:[1,0]
	v_pk_mul_f32 v[228:229], v[228:229], s[20:21] op_sel_hi:[1,0]
	v_pk_mul_f32 v[222:223], v[98:99], v[222:223]
	v_pk_mul_f32 v[224:225], v[100:101], v[224:225]
	v_pk_mul_f32 v[226:227], v[94:95], v[226:227]
	v_pk_mul_f32 v[228:229], v[96:97], v[228:229]
	v_cvt_pk_bf16_f32 v144, v222, v223
	v_cvt_pk_bf16_f32 v145, v224, v225
	v_cvt_pk_bf16_f32 v146, v226, v227
	v_cvt_pk_bf16_f32 v147, v228, v229
	ds_bpermute_b32 v250, v241, v144
	ds_bpermute_b32 v251, v241, v145
	ds_bpermute_b32 v252, v241, v146
	ds_bpermute_b32 v253, v241, v147
	s_waitcnt lgkmcnt(4)
	global_store_dwordx4 v[140:141], v[194:197], off
	s_mov_b64 s[2:3], 0x8000
	v_lshl_add_u64 v[142:143], v[138:139], 0, s[2:3]
	v_cvt_f32_ubyte0_e32 v182, v154
	v_cvt_f32_ubyte1_e32 v183, v154
	v_cvt_f32_ubyte2_e32 v184, v154
	v_cvt_f32_ubyte3_e32 v185, v154
	v_cvt_f32_ubyte0_e32 v186, v155
	v_cvt_f32_ubyte1_e32 v187, v155
	v_cvt_f32_ubyte2_e32 v188, v155
	v_cvt_f32_ubyte3_e32 v189, v155
	v_pk_mul_f32 v[182:183], v[182:183], s[20:21] op_sel_hi:[1,0]
	v_pk_mul_f32 v[184:185], v[184:185], s[20:21] op_sel_hi:[1,0]
	v_pk_mul_f32 v[186:187], v[186:187], s[20:21] op_sel_hi:[1,0]
	v_pk_mul_f32 v[188:189], v[188:189], s[20:21] op_sel_hi:[1,0]
	v_pk_mul_f32 v[182:183], v[122:123], v[182:183]
	v_pk_mul_f32 v[184:185], v[124:125], v[184:185]
	v_pk_mul_f32 v[186:187], v[118:119], v[186:187]
	v_pk_mul_f32 v[188:189], v[120:121], v[188:189]
	v_cvt_pk_bf16_f32 v190, v182, v183
	v_cvt_pk_bf16_f32 v191, v184, v185
	v_cvt_pk_bf16_f32 v192, v186, v187
	v_cvt_pk_bf16_f32 v193, v188, v189
	ds_bpermute_b32 v194, v241, v190
	ds_bpermute_b32 v195, v241, v191
	ds_bpermute_b32 v196, v241, v192
	ds_bpermute_b32 v197, v241, v193
	s_waitcnt lgkmcnt(4)
	global_store_dwordx4 v[140:141], v[250:253], off offset:256
	v_cvt_f32_ubyte0_e32 v222, v156
	v_cvt_f32_ubyte1_e32 v223, v156
	v_cvt_f32_ubyte2_e32 v224, v156
	v_cvt_f32_ubyte3_e32 v225, v156
	v_cvt_f32_ubyte0_e32 v226, v157
	v_cvt_f32_ubyte1_e32 v227, v157
	v_cvt_f32_ubyte2_e32 v228, v157
	v_cvt_f32_ubyte3_e32 v229, v157
	v_pk_mul_f32 v[222:223], v[222:223], s[20:21] op_sel_hi:[1,0]
	v_pk_mul_f32 v[224:225], v[224:225], s[20:21] op_sel_hi:[1,0]
	v_pk_mul_f32 v[226:227], v[226:227], s[20:21] op_sel_hi:[1,0]
	v_pk_mul_f32 v[228:229], v[228:229], s[20:21] op_sel_hi:[1,0]
	v_pk_mul_f32 v[222:223], v[90:91], v[222:223]
	v_pk_mul_f32 v[224:225], v[92:93], v[224:225]
	v_pk_mul_f32 v[226:227], v[86:87], v[226:227]
	v_pk_mul_f32 v[228:229], v[88:89], v[228:229]
	v_cvt_pk_bf16_f32 v144, v222, v223
	v_cvt_pk_bf16_f32 v145, v224, v225
	v_cvt_pk_bf16_f32 v146, v226, v227
	v_cvt_pk_bf16_f32 v147, v228, v229
	ds_bpermute_b32 v250, v241, v144
	ds_bpermute_b32 v251, v241, v145
	ds_bpermute_b32 v252, v241, v146
	ds_bpermute_b32 v253, v241, v147
	s_waitcnt lgkmcnt(4)
	global_store_dwordx4 v[142:143], v[194:197], off
	s_mov_b64 s[2:3], 0x10000
	v_lshl_add_u64 v[140:141], v[138:139], 0, s[2:3]
	v_cvt_f32_ubyte0_e32 v182, v158
	v_cvt_f32_ubyte1_e32 v183, v158
	v_cvt_f32_ubyte2_e32 v184, v158
	v_cvt_f32_ubyte3_e32 v185, v158
	v_cvt_f32_ubyte0_e32 v186, v159
	v_cvt_f32_ubyte1_e32 v187, v159
	v_cvt_f32_ubyte2_e32 v188, v159
	v_cvt_f32_ubyte3_e32 v189, v159
	v_pk_mul_f32 v[182:183], v[182:183], s[20:21] op_sel_hi:[1,0]
	v_pk_mul_f32 v[184:185], v[184:185], s[20:21] op_sel_hi:[1,0]
	v_pk_mul_f32 v[186:187], v[186:187], s[20:21] op_sel_hi:[1,0]
	v_pk_mul_f32 v[188:189], v[188:189], s[20:21] op_sel_hi:[1,0]
	v_pk_mul_f32 v[182:183], v[114:115], v[182:183]
	v_pk_mul_f32 v[184:185], v[116:117], v[184:185]
	v_pk_mul_f32 v[186:187], v[110:111], v[186:187]
	v_pk_mul_f32 v[188:189], v[112:113], v[188:189]
	v_cvt_pk_bf16_f32 v190, v182, v183
	v_cvt_pk_bf16_f32 v191, v184, v185
	v_cvt_pk_bf16_f32 v192, v186, v187
	v_cvt_pk_bf16_f32 v193, v188, v189
	ds_bpermute_b32 v194, v241, v190
	ds_bpermute_b32 v195, v241, v191
	ds_bpermute_b32 v196, v241, v192
	ds_bpermute_b32 v197, v241, v193
	s_waitcnt lgkmcnt(4)
	global_store_dwordx4 v[142:143], v[250:253], off offset:256
	v_cvt_f32_ubyte0_e32 v222, v160
	v_cvt_f32_ubyte1_e32 v223, v160
	v_cvt_f32_ubyte2_e32 v224, v160
	v_cvt_f32_ubyte3_e32 v225, v160
	v_cvt_f32_ubyte0_e32 v226, v161
	v_cvt_f32_ubyte1_e32 v227, v161
	v_cvt_f32_ubyte2_e32 v228, v161
	v_cvt_f32_ubyte3_e32 v229, v161
	v_pk_mul_f32 v[222:223], v[222:223], s[20:21] op_sel_hi:[1,0]
	v_pk_mul_f32 v[224:225], v[224:225], s[20:21] op_sel_hi:[1,0]
	v_pk_mul_f32 v[226:227], v[226:227], s[20:21] op_sel_hi:[1,0]
	v_pk_mul_f32 v[228:229], v[228:229], s[20:21] op_sel_hi:[1,0]
	v_pk_mul_f32 v[222:223], v[82:83], v[222:223]
	v_pk_mul_f32 v[224:225], v[84:85], v[224:225]
	v_pk_mul_f32 v[226:227], v[78:79], v[226:227]
	v_pk_mul_f32 v[228:229], v[80:81], v[228:229]
	v_cvt_pk_bf16_f32 v144, v222, v223
	v_cvt_pk_bf16_f32 v145, v224, v225
	v_cvt_pk_bf16_f32 v146, v226, v227
	v_cvt_pk_bf16_f32 v147, v228, v229
	ds_bpermute_b32 v250, v241, v144
	ds_bpermute_b32 v251, v241, v145
	ds_bpermute_b32 v252, v241, v146
	ds_bpermute_b32 v253, v241, v147
	s_waitcnt lgkmcnt(4)
	global_store_dwordx4 v[140:141], v[194:197], off
	s_mov_b64 s[2:3], 0x18000
	v_lshl_add_u64 v[142:143], v[138:139], 0, s[2:3]
	v_cvt_f32_ubyte0_e32 v182, v162
	v_cvt_f32_ubyte1_e32 v183, v162
	v_cvt_f32_ubyte2_e32 v184, v162
	v_cvt_f32_ubyte3_e32 v185, v162
	v_cvt_f32_ubyte0_e32 v186, v163
	v_cvt_f32_ubyte1_e32 v187, v163
	v_cvt_f32_ubyte2_e32 v188, v163
	v_cvt_f32_ubyte3_e32 v189, v163
	v_pk_mul_f32 v[182:183], v[182:183], s[20:21] op_sel_hi:[1,0]
	v_pk_mul_f32 v[184:185], v[184:185], s[20:21] op_sel_hi:[1,0]
	v_pk_mul_f32 v[186:187], v[186:187], s[20:21] op_sel_hi:[1,0]
	v_pk_mul_f32 v[188:189], v[188:189], s[20:21] op_sel_hi:[1,0]
	v_pk_mul_f32 v[182:183], v[106:107], v[182:183]
	v_pk_mul_f32 v[184:185], v[108:109], v[184:185]
	v_pk_mul_f32 v[186:187], v[102:103], v[186:187]
	v_pk_mul_f32 v[188:189], v[104:105], v[188:189]
	v_cvt_pk_bf16_f32 v190, v182, v183
	v_cvt_pk_bf16_f32 v191, v184, v185
	v_cvt_pk_bf16_f32 v192, v186, v187
	v_cvt_pk_bf16_f32 v193, v188, v189
	ds_bpermute_b32 v194, v241, v190
	ds_bpermute_b32 v195, v241, v191
	ds_bpermute_b32 v196, v241, v192
	ds_bpermute_b32 v197, v241, v193
	s_waitcnt lgkmcnt(4)
	global_store_dwordx4 v[140:141], v[250:253], off offset:256
	v_cvt_f32_ubyte0_e32 v222, v164
	v_cvt_f32_ubyte1_e32 v223, v164
	v_cvt_f32_ubyte2_e32 v224, v164
	v_cvt_f32_ubyte3_e32 v225, v164
	v_cvt_f32_ubyte0_e32 v226, v165
	v_cvt_f32_ubyte1_e32 v227, v165
	v_cvt_f32_ubyte2_e32 v228, v165
	v_cvt_f32_ubyte3_e32 v229, v165
	v_pk_mul_f32 v[222:223], v[222:223], s[20:21] op_sel_hi:[1,0]
	v_pk_mul_f32 v[224:225], v[224:225], s[20:21] op_sel_hi:[1,0]
	v_pk_mul_f32 v[226:227], v[226:227], s[20:21] op_sel_hi:[1,0]
	v_pk_mul_f32 v[228:229], v[228:229], s[20:21] op_sel_hi:[1,0]
	v_pk_mul_f32 v[222:223], v[74:75], v[222:223]
	v_pk_mul_f32 v[224:225], v[76:77], v[224:225]
	v_pk_mul_f32 v[226:227], v[70:71], v[226:227]
	v_pk_mul_f32 v[228:229], v[72:73], v[228:229]
	v_cvt_pk_bf16_f32 v144, v222, v223
	v_cvt_pk_bf16_f32 v145, v224, v225
	v_cvt_pk_bf16_f32 v146, v226, v227
	v_cvt_pk_bf16_f32 v147, v228, v229
	ds_bpermute_b32 v250, v241, v144
	ds_bpermute_b32 v251, v241, v145
	ds_bpermute_b32 v252, v241, v146
	ds_bpermute_b32 v253, v241, v147
	s_waitcnt lgkmcnt(4)
	global_store_dwordx4 v[142:143], v[194:197], off
	s_mov_b64 s[2:3], 0x40000
	v_lshl_add_u64 v[140:141], v[138:139], 0, s[2:3]
	v_cvt_f32_ubyte0_e32 v182, v166
	v_cvt_f32_ubyte1_e32 v183, v166
	v_cvt_f32_ubyte2_e32 v184, v166
	v_cvt_f32_ubyte3_e32 v185, v166
	v_cvt_f32_ubyte0_e32 v186, v167
	v_cvt_f32_ubyte1_e32 v187, v167
	v_cvt_f32_ubyte2_e32 v188, v167
	v_cvt_f32_ubyte3_e32 v189, v167
	v_pk_mul_f32 v[182:183], v[182:183], s[20:21] op_sel_hi:[1,0]
	v_pk_mul_f32 v[184:185], v[184:185], s[20:21] op_sel_hi:[1,0]
	v_pk_mul_f32 v[186:187], v[186:187], s[20:21] op_sel_hi:[1,0]
	v_pk_mul_f32 v[188:189], v[188:189], s[20:21] op_sel_hi:[1,0]
	v_pk_mul_f32 v[182:183], v[66:67], v[182:183]
	v_pk_mul_f32 v[184:185], v[68:69], v[184:185]
	v_pk_mul_f32 v[186:187], v[62:63], v[186:187]
	v_pk_mul_f32 v[188:189], v[64:65], v[188:189]
	v_cvt_pk_bf16_f32 v190, v182, v183
	v_cvt_pk_bf16_f32 v191, v184, v185
	v_cvt_pk_bf16_f32 v192, v186, v187
	v_cvt_pk_bf16_f32 v193, v188, v189
	ds_bpermute_b32 v194, v241, v190
	ds_bpermute_b32 v195, v241, v191
	ds_bpermute_b32 v196, v241, v192
	ds_bpermute_b32 v197, v241, v193
	s_waitcnt lgkmcnt(4)
	global_store_dwordx4 v[142:143], v[250:253], off offset:256
	v_cvt_f32_ubyte0_e32 v222, v168
	v_cvt_f32_ubyte1_e32 v223, v168
	v_cvt_f32_ubyte2_e32 v224, v168
	v_cvt_f32_ubyte3_e32 v225, v168
	v_cvt_f32_ubyte0_e32 v226, v169
	v_cvt_f32_ubyte1_e32 v227, v169
	v_cvt_f32_ubyte2_e32 v228, v169
	v_cvt_f32_ubyte3_e32 v229, v169
	v_pk_mul_f32 v[222:223], v[222:223], s[20:21] op_sel_hi:[1,0]
	v_pk_mul_f32 v[224:225], v[224:225], s[20:21] op_sel_hi:[1,0]
	v_pk_mul_f32 v[226:227], v[226:227], s[20:21] op_sel_hi:[1,0]
	v_pk_mul_f32 v[228:229], v[228:229], s[20:21] op_sel_hi:[1,0]
	v_pk_mul_f32 v[222:223], v[34:35], v[222:223]
	v_pk_mul_f32 v[224:225], v[36:37], v[224:225]
	v_pk_mul_f32 v[226:227], v[30:31], v[226:227]
	v_pk_mul_f32 v[228:229], v[32:33], v[228:229]
	v_cvt_pk_bf16_f32 v144, v222, v223
	v_cvt_pk_bf16_f32 v145, v224, v225
	v_cvt_pk_bf16_f32 v146, v226, v227
	v_cvt_pk_bf16_f32 v147, v228, v229
	ds_bpermute_b32 v250, v241, v144
	ds_bpermute_b32 v251, v241, v145
	ds_bpermute_b32 v252, v241, v146
	ds_bpermute_b32 v253, v241, v147
	s_waitcnt lgkmcnt(4)
	global_store_dwordx4 v[140:141], v[194:197], off
	s_mov_b64 s[2:3], 0x48000
	v_lshl_add_u64 v[142:143], v[138:139], 0, s[2:3]
	v_cvt_f32_ubyte0_e32 v182, v170
	v_cvt_f32_ubyte1_e32 v183, v170
	v_cvt_f32_ubyte2_e32 v184, v170
	v_cvt_f32_ubyte3_e32 v185, v170
	v_cvt_f32_ubyte0_e32 v186, v171
	v_cvt_f32_ubyte1_e32 v187, v171
	v_cvt_f32_ubyte2_e32 v188, v171
	v_cvt_f32_ubyte3_e32 v189, v171
	v_pk_mul_f32 v[182:183], v[182:183], s[20:21] op_sel_hi:[1,0]
	v_pk_mul_f32 v[184:185], v[184:185], s[20:21] op_sel_hi:[1,0]
	v_pk_mul_f32 v[186:187], v[186:187], s[20:21] op_sel_hi:[1,0]
	v_pk_mul_f32 v[188:189], v[188:189], s[20:21] op_sel_hi:[1,0]
	v_pk_mul_f32 v[182:183], v[58:59], v[182:183]
	v_pk_mul_f32 v[184:185], v[60:61], v[184:185]
	v_pk_mul_f32 v[186:187], v[54:55], v[186:187]
	v_pk_mul_f32 v[188:189], v[56:57], v[188:189]
	v_cvt_pk_bf16_f32 v190, v182, v183
	v_cvt_pk_bf16_f32 v191, v184, v185
	v_cvt_pk_bf16_f32 v192, v186, v187
	v_cvt_pk_bf16_f32 v193, v188, v189
	ds_bpermute_b32 v194, v241, v190
	ds_bpermute_b32 v195, v241, v191
	ds_bpermute_b32 v196, v241, v192
	ds_bpermute_b32 v197, v241, v193
	s_waitcnt lgkmcnt(4)
	global_store_dwordx4 v[140:141], v[250:253], off offset:256
	v_cvt_f32_ubyte0_e32 v222, v172
	v_cvt_f32_ubyte1_e32 v223, v172
	v_cvt_f32_ubyte2_e32 v224, v172
	v_cvt_f32_ubyte3_e32 v225, v172
	v_cvt_f32_ubyte0_e32 v226, v173
	v_cvt_f32_ubyte1_e32 v227, v173
	v_cvt_f32_ubyte2_e32 v228, v173
	v_cvt_f32_ubyte3_e32 v229, v173
	v_pk_mul_f32 v[222:223], v[222:223], s[20:21] op_sel_hi:[1,0]
	v_pk_mul_f32 v[224:225], v[224:225], s[20:21] op_sel_hi:[1,0]
	v_pk_mul_f32 v[226:227], v[226:227], s[20:21] op_sel_hi:[1,0]
	v_pk_mul_f32 v[228:229], v[228:229], s[20:21] op_sel_hi:[1,0]
	v_pk_mul_f32 v[222:223], v[26:27], v[222:223]
	v_pk_mul_f32 v[224:225], v[28:29], v[224:225]
	v_pk_mul_f32 v[226:227], v[22:23], v[226:227]
	v_pk_mul_f32 v[228:229], v[24:25], v[228:229]
	v_cvt_pk_bf16_f32 v144, v222, v223
	v_cvt_pk_bf16_f32 v145, v224, v225
	v_cvt_pk_bf16_f32 v146, v226, v227
	v_cvt_pk_bf16_f32 v147, v228, v229
	ds_bpermute_b32 v250, v241, v144
	ds_bpermute_b32 v251, v241, v145
	ds_bpermute_b32 v252, v241, v146
	ds_bpermute_b32 v253, v241, v147
	s_waitcnt lgkmcnt(4)
	global_store_dwordx4 v[142:143], v[194:197], off
	s_mov_b64 s[2:3], 0x50000
	v_lshl_add_u64 v[140:141], v[138:139], 0, s[2:3]
	v_cvt_f32_ubyte0_e32 v182, v174
	v_cvt_f32_ubyte1_e32 v183, v174
	v_cvt_f32_ubyte2_e32 v184, v174
	v_cvt_f32_ubyte3_e32 v185, v174
	v_cvt_f32_ubyte0_e32 v186, v175
	v_cvt_f32_ubyte1_e32 v187, v175
	v_cvt_f32_ubyte2_e32 v188, v175
	v_cvt_f32_ubyte3_e32 v189, v175
	v_pk_mul_f32 v[182:183], v[182:183], s[20:21] op_sel_hi:[1,0]
	v_pk_mul_f32 v[184:185], v[184:185], s[20:21] op_sel_hi:[1,0]
	v_pk_mul_f32 v[186:187], v[186:187], s[20:21] op_sel_hi:[1,0]
	v_pk_mul_f32 v[188:189], v[188:189], s[20:21] op_sel_hi:[1,0]
	v_pk_mul_f32 v[182:183], v[50:51], v[182:183]
	v_pk_mul_f32 v[184:185], v[52:53], v[184:185]
	v_pk_mul_f32 v[186:187], v[46:47], v[186:187]
	v_pk_mul_f32 v[188:189], v[48:49], v[188:189]
	v_cvt_pk_bf16_f32 v190, v182, v183
	v_cvt_pk_bf16_f32 v191, v184, v185
	v_cvt_pk_bf16_f32 v192, v186, v187
	v_cvt_pk_bf16_f32 v193, v188, v189
	ds_bpermute_b32 v194, v241, v190
	ds_bpermute_b32 v195, v241, v191
	ds_bpermute_b32 v196, v241, v192
	ds_bpermute_b32 v197, v241, v193
	s_waitcnt lgkmcnt(4)
	global_store_dwordx4 v[142:143], v[250:253], off offset:256
	v_cvt_f32_ubyte0_e32 v222, v176
	v_cvt_f32_ubyte1_e32 v223, v176
	v_cvt_f32_ubyte2_e32 v224, v176
	v_cvt_f32_ubyte3_e32 v225, v176
	v_cvt_f32_ubyte0_e32 v226, v177
	v_cvt_f32_ubyte1_e32 v227, v177
	v_cvt_f32_ubyte2_e32 v228, v177
	v_cvt_f32_ubyte3_e32 v229, v177
	v_pk_mul_f32 v[222:223], v[222:223], s[20:21] op_sel_hi:[1,0]
	v_pk_mul_f32 v[224:225], v[224:225], s[20:21] op_sel_hi:[1,0]
	v_pk_mul_f32 v[226:227], v[226:227], s[20:21] op_sel_hi:[1,0]
	v_pk_mul_f32 v[228:229], v[228:229], s[20:21] op_sel_hi:[1,0]
	v_pk_mul_f32 v[222:223], v[18:19], v[222:223]
	v_pk_mul_f32 v[224:225], v[20:21], v[224:225]
	v_pk_mul_f32 v[226:227], v[14:15], v[226:227]
	v_pk_mul_f32 v[228:229], v[16:17], v[228:229]
	v_cvt_pk_bf16_f32 v144, v222, v223
	v_cvt_pk_bf16_f32 v145, v224, v225
	v_cvt_pk_bf16_f32 v146, v226, v227
	v_cvt_pk_bf16_f32 v147, v228, v229
	ds_bpermute_b32 v250, v241, v144
	ds_bpermute_b32 v251, v241, v145
	ds_bpermute_b32 v252, v241, v146
	ds_bpermute_b32 v253, v241, v147
	s_waitcnt lgkmcnt(4)
	global_store_dwordx4 v[140:141], v[194:197], off
	s_mov_b64 s[2:3], 0x58000
	v_lshl_add_u64 v[142:143], v[138:139], 0, s[2:3]
	v_cvt_f32_ubyte0_e32 v182, v178
	v_cvt_f32_ubyte1_e32 v183, v178
	v_cvt_f32_ubyte2_e32 v184, v178
	v_cvt_f32_ubyte3_e32 v185, v178
	v_cvt_f32_ubyte0_e32 v186, v179
	v_cvt_f32_ubyte1_e32 v187, v179
	v_cvt_f32_ubyte2_e32 v188, v179
	v_cvt_f32_ubyte3_e32 v189, v179
	v_pk_mul_f32 v[182:183], v[182:183], s[20:21] op_sel_hi:[1,0]
	v_pk_mul_f32 v[184:185], v[184:185], s[20:21] op_sel_hi:[1,0]
	v_pk_mul_f32 v[186:187], v[186:187], s[20:21] op_sel_hi:[1,0]
	v_pk_mul_f32 v[188:189], v[188:189], s[20:21] op_sel_hi:[1,0]
	v_pk_mul_f32 v[182:183], v[42:43], v[182:183]
	v_pk_mul_f32 v[184:185], v[44:45], v[184:185]
	v_pk_mul_f32 v[186:187], v[38:39], v[186:187]
	v_pk_mul_f32 v[188:189], v[40:41], v[188:189]
	v_cvt_pk_bf16_f32 v190, v182, v183
	v_cvt_pk_bf16_f32 v191, v184, v185
	v_cvt_pk_bf16_f32 v192, v186, v187
	v_cvt_pk_bf16_f32 v193, v188, v189
	ds_bpermute_b32 v194, v241, v190
	ds_bpermute_b32 v195, v241, v191
	ds_bpermute_b32 v196, v241, v192
	ds_bpermute_b32 v197, v241, v193
	s_waitcnt lgkmcnt(4)
	global_store_dwordx4 v[140:141], v[250:253], off offset:256
	v_cvt_f32_ubyte0_e32 v222, v180
	v_cvt_f32_ubyte1_e32 v223, v180
	v_cvt_f32_ubyte2_e32 v224, v180
	v_cvt_f32_ubyte3_e32 v225, v180
	v_cvt_f32_ubyte0_e32 v226, v181
	v_cvt_f32_ubyte1_e32 v227, v181
	v_cvt_f32_ubyte2_e32 v228, v181
	v_cvt_f32_ubyte3_e32 v229, v181
	v_pk_mul_f32 v[222:223], v[222:223], s[20:21] op_sel_hi:[1,0]
	v_pk_mul_f32 v[224:225], v[224:225], s[20:21] op_sel_hi:[1,0]
	v_pk_mul_f32 v[226:227], v[226:227], s[20:21] op_sel_hi:[1,0]
	v_pk_mul_f32 v[228:229], v[228:229], s[20:21] op_sel_hi:[1,0]
	v_pk_mul_f32 v[222:223], v[10:11], v[222:223]
	v_pk_mul_f32 v[224:225], v[12:13], v[224:225]
	v_pk_mul_f32 v[226:227], v[6:7], v[226:227]
	v_pk_mul_f32 v[228:229], v[8:9], v[228:229]
	v_cvt_pk_bf16_f32 v144, v222, v223
	v_cvt_pk_bf16_f32 v145, v224, v225
	v_cvt_pk_bf16_f32 v146, v226, v227
	v_cvt_pk_bf16_f32 v147, v228, v229
	ds_bpermute_b32 v250, v241, v144
	ds_bpermute_b32 v251, v241, v145
	ds_bpermute_b32 v252, v241, v146
	ds_bpermute_b32 v253, v241, v147
	s_waitcnt lgkmcnt(4)
	global_store_dwordx4 v[142:143], v[194:197], off
	s_waitcnt lgkmcnt(0)
	global_store_dwordx4 v[142:143], v[250:253], off offset:256
	s_cbranch_execnz .LBB0_552
